# attention item epilogue: permlane32_swap pairs, 8 dwordx4 output stores per lane instead of 16 dwordx2
# speedup vs baseline: 1.0148x; 1.0008x over previous
.LBB0_1065:
	v_mov_b32_e32 v0, v33
	s_getreg_b32 s2, hwreg(HW_REG_HW_ID, 0, 6)
	s_lshl_b32 s2, s2, 2
	s_and_b32 s2, s2, 0xfc
	s_add_i32 s2, s2, 0
	s_add_i32 s2, s2, 0x21100
	v_mov_b32_e32 v1, s2
	ds_read_b32 v1, v1
	v_mbcnt_lo_u32_b32 v0, -1, v0
	v_mbcnt_hi_u32_b32 v0, -1, v0
	s_mov_b64 s[2:3], 0
	v_lshlrev_b32_e32 v36, 16, v203
	s_waitcnt lgkmcnt(0)
	v_lshl_or_b32 v2, v1, 6, v0
	s_add_u32 s2, s76, s2
	s_addc_u32 s3, s77, s3
	s_add_i32 s96, s96, s87
	v_and_or_b32 v0, v2, 31, s96
	v_or_b32_e32 v32, s97, v0
	v_lshlrev_b64 v[0:1], 12, v[32:33]
	v_lshl_add_u64 v[0:1], s[2:3], 0, v[0:1]
	v_lshrrev_b32_e32 v2, 2, v2
	v_lshl_add_u64 v[0:1], s[84:85], 1, v[0:1]
	v_and_b32_e32 v32, 8, v2
	v_lshl_add_u64 v[2:3], v[0:1], 0, v[32:33]
	s_mov_b64 s[2:3], 0x25e51000
	v_lshl_add_u64 v[0:1], v[2:3], 0, s[2:3]
	s_mov_b32 s2, 0x25e51000
	v_add_co_u32_e32 v4, vcc, s2, v2
	v_and_b32_e32 v37, 0xffff0000, v203
	s_nop 0
	v_addc_co_u32_e32 v5, vcc, 0, v3, vcc
	global_load_dwordx2 v[34:35], v[4:5], off
	global_load_dwordx2 v[30:31], v[0:1], off offset:16
	global_load_dwordx2 v[28:29], v[0:1], off offset:32
	global_load_dwordx2 v[26:27], v[0:1], off offset:48
	global_load_dwordx2 v[24:25], v[0:1], off offset:64
	global_load_dwordx2 v[22:23], v[0:1], off offset:80
	global_load_dwordx2 v[20:21], v[0:1], off offset:96
	global_load_dwordx2 v[18:19], v[0:1], off offset:112
	global_load_dwordx2 v[16:17], v[0:1], off offset:128
	global_load_dwordx2 v[14:15], v[0:1], off offset:144
	global_load_dwordx2 v[12:13], v[0:1], off offset:160
	global_load_dwordx2 v[10:11], v[0:1], off offset:176
	global_load_dwordx2 v[8:9], v[0:1], off offset:192
	global_load_dwordx2 v[6:7], v[0:1], off offset:208
	global_load_dwordx2 v[4:5], v[0:1], off offset:224
	s_nop 0
	global_load_dwordx2 v[0:1], v[0:1], off offset:240
	s_mov_b32 s2, 0x29e51000
	v_add_co_u32_e32 v2, vcc, s2, v2
	s_waitcnt vmcnt(0)
	v_lshlrev_b32_e32 v38, 16, v34
	v_mul_f32_e32 v32, 0xbfb8aa3b, v38
	v_exp_f32_e32 v32, v32
	v_and_b32_e32 v39, 0xffff0000, v34
	v_addc_co_u32_e32 v3, vcc, 0, v3, vcc
	v_mbcnt_lo_u32_b32 v252, -1, 0
	v_mbcnt_hi_u32_b32 v252, -1, v252
	v_and_b32_e32 v252, 32, v252
	v_lshrrev_b32_e32 v252, 2, v252
	v_mov_b32_e32 v253, 0
	v_lshl_add_u64 v[228:229], v[2:3], 0, v[252:253]
	v_add_f32_e32 v32, 1.0, v32
	v_rcp_f32_e32 v40, v32
	v_mul_f32_e32 v32, 0xbfb8aa3b, v39
	v_exp_f32_e32 v32, v32
	s_nop 0
	v_add_f32_e32 v32, 1.0, v32
	v_rcp_f32_e32 v41, v32
	s_nop 0
	v_pk_mul_f32 v[38:39], v[40:41], v[38:39]
	s_nop 0
	v_pk_mul_f32 v[36:37], v[38:39], v[36:37]
	v_lshlrev_b32_e32 v38, 16, v35
	v_mul_f32_e32 v32, 0xbfb8aa3b, v38
	v_exp_f32_e32 v32, v32
	v_and_b32_e32 v39, 0xffff0000, v35
	v_cvt_pk_bf16_f32 v34, v36, v37
	v_lshlrev_b32_e32 v36, 16, v202
	v_add_f32_e32 v32, 1.0, v32
	v_rcp_f32_e32 v40, v32
	v_mul_f32_e32 v32, 0xbfb8aa3b, v39
	v_exp_f32_e32 v32, v32
	v_and_b32_e32 v37, 0xffff0000, v202
	v_add_f32_e32 v32, 1.0, v32
	v_rcp_f32_e32 v41, v32
	s_nop 0
	v_pk_mul_f32 v[38:39], v[40:41], v[38:39]
	s_nop 0
	v_pk_mul_f32 v[36:37], v[38:39], v[36:37]
	s_nop 0
	v_cvt_pk_bf16_f32 v35, v36, v37
	v_lshlrev_b32_e32 v36, 16, v30
	v_and_b32_e32 v37, 0xffff0000, v30
	v_mul_f32_e32 v30, 0xbfb8aa3b, v36
	v_exp_f32_e32 v30, v30
	v_mov_b32_e32 v212, v34
	v_mov_b32_e32 v213, v35
	v_lshlrev_b32_e32 v34, 16, v201
	v_and_b32_e32 v35, 0xffff0000, v201
	v_add_f32_e32 v30, 1.0, v30
	v_rcp_f32_e32 v38, v30
	v_mul_f32_e32 v30, 0xbfb8aa3b, v37
	v_exp_f32_e32 v30, v30
	s_nop 0
	v_add_f32_e32 v30, 1.0, v30
	v_rcp_f32_e32 v39, v30
	s_nop 0
	v_pk_mul_f32 v[36:37], v[38:39], v[36:37]
	s_nop 0
	v_pk_mul_f32 v[34:35], v[36:37], v[34:35]
	v_lshlrev_b32_e32 v36, 16, v31
	v_and_b32_e32 v37, 0xffff0000, v31
	v_mul_f32_e32 v31, 0xbfb8aa3b, v36
	v_exp_f32_e32 v31, v31
	v_cvt_pk_bf16_f32 v30, v34, v35
	v_lshlrev_b32_e32 v34, 16, v200
	v_and_b32_e32 v35, 0xffff0000, v200
	v_add_f32_e32 v31, 1.0, v31
	v_rcp_f32_e32 v38, v31
	v_mul_f32_e32 v31, 0xbfb8aa3b, v37
	v_exp_f32_e32 v31, v31
	s_nop 0
	v_add_f32_e32 v31, 1.0, v31
	v_rcp_f32_e32 v39, v31
	s_nop 0
	v_pk_mul_f32 v[36:37], v[38:39], v[36:37]
	s_nop 0
	v_pk_mul_f32 v[34:35], v[36:37], v[34:35]
	s_nop 0
	v_cvt_pk_bf16_f32 v31, v34, v35
	v_lshlrev_b32_e32 v34, 16, v28
	v_and_b32_e32 v35, 0xffff0000, v28
	v_mul_f32_e32 v28, 0xbfb8aa3b, v34
	v_exp_f32_e32 v28, v28
	v_mov_b32_e32 v214, v30
	v_mov_b32_e32 v215, v31
	s_nop 1
	v_permlane32_swap_b32_e32 v212, v214
	v_permlane32_swap_b32_e32 v213, v215
	global_store_dwordx4 v[228:229], v[212:215], off
	v_lshlrev_b32_e32 v30, 16, v199
	v_and_b32_e32 v31, 0xffff0000, v199
	v_add_f32_e32 v28, 1.0, v28
	v_rcp_f32_e32 v36, v28
	v_mul_f32_e32 v28, 0xbfb8aa3b, v35
	v_exp_f32_e32 v28, v28
	s_nop 0
	v_add_f32_e32 v28, 1.0, v28
	v_rcp_f32_e32 v37, v28
	s_nop 0
	v_pk_mul_f32 v[34:35], v[36:37], v[34:35]
	s_nop 0
	v_pk_mul_f32 v[30:31], v[34:35], v[30:31]
	v_lshlrev_b32_e32 v34, 16, v29
	v_and_b32_e32 v35, 0xffff0000, v29
	v_mul_f32_e32 v29, 0xbfb8aa3b, v34
	v_exp_f32_e32 v29, v29
	v_cvt_pk_bf16_f32 v28, v30, v31
	v_lshlrev_b32_e32 v30, 16, v198
	v_and_b32_e32 v31, 0xffff0000, v198
	v_add_f32_e32 v29, 1.0, v29
	v_rcp_f32_e32 v36, v29
	v_mul_f32_e32 v29, 0xbfb8aa3b, v35
	v_exp_f32_e32 v29, v29
	s_nop 0
	v_add_f32_e32 v29, 1.0, v29
	v_rcp_f32_e32 v37, v29
	s_nop 0
	v_pk_mul_f32 v[34:35], v[36:37], v[34:35]
	s_nop 0
	v_pk_mul_f32 v[30:31], v[34:35], v[30:31]
	s_nop 0
	v_cvt_pk_bf16_f32 v29, v30, v31
	v_lshlrev_b32_e32 v30, 16, v26
	v_and_b32_e32 v31, 0xffff0000, v26
	v_mul_f32_e32 v26, 0xbfb8aa3b, v30
	v_exp_f32_e32 v26, v26
	v_mov_b32_e32 v216, v28
	v_mov_b32_e32 v217, v29
	v_lshlrev_b32_e32 v28, 16, v197
	v_and_b32_e32 v29, 0xffff0000, v197
	v_add_f32_e32 v26, 1.0, v26
	v_rcp_f32_e32 v34, v26
	v_mul_f32_e32 v26, 0xbfb8aa3b, v31
	v_exp_f32_e32 v26, v26
	s_nop 0
	v_add_f32_e32 v26, 1.0, v26
	v_rcp_f32_e32 v35, v26
	s_nop 0
	v_pk_mul_f32 v[30:31], v[34:35], v[30:31]
	s_nop 0
	v_pk_mul_f32 v[28:29], v[30:31], v[28:29]
	v_lshlrev_b32_e32 v30, 16, v27
	v_and_b32_e32 v31, 0xffff0000, v27
	v_mul_f32_e32 v27, 0xbfb8aa3b, v30
	v_exp_f32_e32 v27, v27
	v_cvt_pk_bf16_f32 v26, v28, v29
	v_lshlrev_b32_e32 v28, 16, v196
	v_and_b32_e32 v29, 0xffff0000, v196
	v_add_f32_e32 v27, 1.0, v27
	v_rcp_f32_e32 v34, v27
	v_mul_f32_e32 v27, 0xbfb8aa3b, v31
	v_exp_f32_e32 v27, v27
	s_nop 0
	v_add_f32_e32 v27, 1.0, v27
	v_rcp_f32_e32 v35, v27
	s_nop 0
	v_pk_mul_f32 v[30:31], v[34:35], v[30:31]
	s_nop 0
	v_pk_mul_f32 v[28:29], v[30:31], v[28:29]
	s_nop 0
	v_cvt_pk_bf16_f32 v27, v28, v29
	v_lshlrev_b32_e32 v28, 16, v24
	v_and_b32_e32 v29, 0xffff0000, v24
	v_mul_f32_e32 v24, 0xbfb8aa3b, v28
	v_exp_f32_e32 v24, v24
	v_mov_b32_e32 v218, v26
	v_mov_b32_e32 v219, v27
	s_nop 1
	v_permlane32_swap_b32_e32 v216, v218
	v_permlane32_swap_b32_e32 v217, v219
	global_store_dwordx4 v[228:229], v[216:219], off offset:32
	v_lshlrev_b32_e32 v26, 16, v195
	v_and_b32_e32 v27, 0xffff0000, v195
	v_add_f32_e32 v24, 1.0, v24
	v_rcp_f32_e32 v30, v24
	v_mul_f32_e32 v24, 0xbfb8aa3b, v29
	v_exp_f32_e32 v24, v24
	s_nop 0
	v_add_f32_e32 v24, 1.0, v24
	v_rcp_f32_e32 v31, v24
	s_nop 0
	v_pk_mul_f32 v[28:29], v[30:31], v[28:29]
	s_nop 0
	v_pk_mul_f32 v[26:27], v[28:29], v[26:27]
	v_lshlrev_b32_e32 v28, 16, v25
	v_and_b32_e32 v29, 0xffff0000, v25
	v_mul_f32_e32 v25, 0xbfb8aa3b, v28
	v_exp_f32_e32 v25, v25
	v_cvt_pk_bf16_f32 v24, v26, v27
	v_lshlrev_b32_e32 v26, 16, v194
	v_and_b32_e32 v27, 0xffff0000, v194
	v_add_f32_e32 v25, 1.0, v25
	v_rcp_f32_e32 v30, v25
	v_mul_f32_e32 v25, 0xbfb8aa3b, v29
	v_exp_f32_e32 v25, v25
	s_nop 0
	v_add_f32_e32 v25, 1.0, v25
	v_rcp_f32_e32 v31, v25
	s_nop 0
	v_pk_mul_f32 v[28:29], v[30:31], v[28:29]
	s_nop 0
	v_pk_mul_f32 v[26:27], v[28:29], v[26:27]
	s_nop 0
	v_cvt_pk_bf16_f32 v25, v26, v27
	v_lshlrev_b32_e32 v26, 16, v22
	v_and_b32_e32 v27, 0xffff0000, v22
	v_mul_f32_e32 v22, 0xbfb8aa3b, v26
	v_exp_f32_e32 v22, v22
	v_mov_b32_e32 v220, v24
	v_mov_b32_e32 v221, v25
	v_lshlrev_b32_e32 v24, 16, v193
	v_and_b32_e32 v25, 0xffff0000, v193
	v_add_f32_e32 v22, 1.0, v22
	v_rcp_f32_e32 v28, v22
	v_mul_f32_e32 v22, 0xbfb8aa3b, v27
	v_exp_f32_e32 v22, v22
	s_nop 0
	v_add_f32_e32 v22, 1.0, v22
	v_rcp_f32_e32 v29, v22
	s_nop 0
	v_pk_mul_f32 v[26:27], v[28:29], v[26:27]
	s_nop 0
	v_pk_mul_f32 v[24:25], v[26:27], v[24:25]
	v_lshlrev_b32_e32 v26, 16, v23
	v_and_b32_e32 v27, 0xffff0000, v23
	v_mul_f32_e32 v23, 0xbfb8aa3b, v26
	v_exp_f32_e32 v23, v23
	v_cvt_pk_bf16_f32 v22, v24, v25
	v_lshlrev_b32_e32 v24, 16, v192
	v_and_b32_e32 v25, 0xffff0000, v192
	v_add_f32_e32 v23, 1.0, v23
	v_rcp_f32_e32 v28, v23
	v_mul_f32_e32 v23, 0xbfb8aa3b, v27
	v_exp_f32_e32 v23, v23
	s_nop 0
	v_add_f32_e32 v23, 1.0, v23
	v_rcp_f32_e32 v29, v23
	s_nop 0
	v_pk_mul_f32 v[26:27], v[28:29], v[26:27]
	s_nop 0
	v_pk_mul_f32 v[24:25], v[26:27], v[24:25]
	s_nop 0
	v_cvt_pk_bf16_f32 v23, v24, v25
	v_lshlrev_b32_e32 v24, 16, v20
	v_and_b32_e32 v25, 0xffff0000, v20
	v_mul_f32_e32 v20, 0xbfb8aa3b, v24
	v_exp_f32_e32 v20, v20
	v_mov_b32_e32 v222, v22
	v_mov_b32_e32 v223, v23
	s_nop 1
	v_permlane32_swap_b32_e32 v220, v222
	v_permlane32_swap_b32_e32 v221, v223
	global_store_dwordx4 v[228:229], v[220:223], off offset:64
	v_lshlrev_b32_e32 v22, 16, v191
	v_and_b32_e32 v23, 0xffff0000, v191
	v_add_f32_e32 v20, 1.0, v20
	v_rcp_f32_e32 v26, v20
	v_mul_f32_e32 v20, 0xbfb8aa3b, v25
	v_exp_f32_e32 v20, v20
	s_nop 0
	v_add_f32_e32 v20, 1.0, v20
	v_rcp_f32_e32 v27, v20
	s_nop 0
	v_pk_mul_f32 v[24:25], v[26:27], v[24:25]
	s_nop 0
	v_pk_mul_f32 v[22:23], v[24:25], v[22:23]
	v_lshlrev_b32_e32 v24, 16, v21
	v_and_b32_e32 v25, 0xffff0000, v21
	v_mul_f32_e32 v21, 0xbfb8aa3b, v24
	v_exp_f32_e32 v21, v21
	v_cvt_pk_bf16_f32 v20, v22, v23
	v_lshlrev_b32_e32 v22, 16, v190
	v_and_b32_e32 v23, 0xffff0000, v190
	v_add_f32_e32 v21, 1.0, v21
	v_rcp_f32_e32 v26, v21
	v_mul_f32_e32 v21, 0xbfb8aa3b, v25
	v_exp_f32_e32 v21, v21
	s_nop 0
	v_add_f32_e32 v21, 1.0, v21
	v_rcp_f32_e32 v27, v21
	s_nop 0
	v_pk_mul_f32 v[24:25], v[26:27], v[24:25]
	s_nop 0
	v_pk_mul_f32 v[22:23], v[24:25], v[22:23]
	s_nop 0
	v_cvt_pk_bf16_f32 v21, v22, v23
	v_lshlrev_b32_e32 v22, 16, v18
	v_and_b32_e32 v23, 0xffff0000, v18
	v_mul_f32_e32 v18, 0xbfb8aa3b, v22
	v_exp_f32_e32 v18, v18
	v_mov_b32_e32 v224, v20
	v_mov_b32_e32 v225, v21
	v_lshlrev_b32_e32 v20, 16, v189
	v_and_b32_e32 v21, 0xffff0000, v189
	v_add_f32_e32 v18, 1.0, v18
	v_rcp_f32_e32 v24, v18
	v_mul_f32_e32 v18, 0xbfb8aa3b, v23
	v_exp_f32_e32 v18, v18
	s_nop 0
	v_add_f32_e32 v18, 1.0, v18
	v_rcp_f32_e32 v25, v18
	s_nop 0
	v_pk_mul_f32 v[22:23], v[24:25], v[22:23]
	s_nop 0
	v_pk_mul_f32 v[20:21], v[22:23], v[20:21]
	v_lshlrev_b32_e32 v22, 16, v19
	v_and_b32_e32 v23, 0xffff0000, v19
	v_mul_f32_e32 v19, 0xbfb8aa3b, v22
	v_exp_f32_e32 v19, v19
	v_cvt_pk_bf16_f32 v18, v20, v21
	v_lshlrev_b32_e32 v20, 16, v188
	v_and_b32_e32 v21, 0xffff0000, v188
	v_add_f32_e32 v19, 1.0, v19
	v_rcp_f32_e32 v24, v19
	v_mul_f32_e32 v19, 0xbfb8aa3b, v23
	v_exp_f32_e32 v19, v19
	s_nop 0
	v_add_f32_e32 v19, 1.0, v19
	v_rcp_f32_e32 v25, v19
	s_nop 0
	v_pk_mul_f32 v[22:23], v[24:25], v[22:23]
	s_nop 0
	v_pk_mul_f32 v[20:21], v[22:23], v[20:21]
	s_nop 0
	v_cvt_pk_bf16_f32 v19, v20, v21
	v_lshlrev_b32_e32 v20, 16, v16
	v_and_b32_e32 v21, 0xffff0000, v16
	v_mul_f32_e32 v16, 0xbfb8aa3b, v20
	v_exp_f32_e32 v16, v16
	v_mov_b32_e32 v226, v18
	v_mov_b32_e32 v227, v19
	s_nop 1
	v_permlane32_swap_b32_e32 v224, v226
	v_permlane32_swap_b32_e32 v225, v227
	global_store_dwordx4 v[228:229], v[224:227], off offset:96
	v_lshlrev_b32_e32 v18, 16, v187
	v_and_b32_e32 v19, 0xffff0000, v187
	v_add_f32_e32 v16, 1.0, v16
	v_rcp_f32_e32 v22, v16
	v_mul_f32_e32 v16, 0xbfb8aa3b, v21
	v_exp_f32_e32 v16, v16
	s_nop 0
	v_add_f32_e32 v16, 1.0, v16
	v_rcp_f32_e32 v23, v16
	s_nop 0
	v_pk_mul_f32 v[20:21], v[22:23], v[20:21]
	s_nop 0
	v_pk_mul_f32 v[18:19], v[20:21], v[18:19]
	v_lshlrev_b32_e32 v20, 16, v17
	v_and_b32_e32 v21, 0xffff0000, v17
	v_mul_f32_e32 v17, 0xbfb8aa3b, v20
	v_exp_f32_e32 v17, v17
	v_cvt_pk_bf16_f32 v16, v18, v19
	v_lshlrev_b32_e32 v18, 16, v186
	v_and_b32_e32 v19, 0xffff0000, v186
	v_add_f32_e32 v17, 1.0, v17
	v_rcp_f32_e32 v22, v17
	v_mul_f32_e32 v17, 0xbfb8aa3b, v21
	v_exp_f32_e32 v17, v17
	s_nop 0
	v_add_f32_e32 v17, 1.0, v17
	v_rcp_f32_e32 v23, v17
	s_nop 0
	v_pk_mul_f32 v[20:21], v[22:23], v[20:21]
	s_nop 0
	v_pk_mul_f32 v[18:19], v[20:21], v[18:19]
	s_nop 0
	v_cvt_pk_bf16_f32 v17, v18, v19
	v_lshlrev_b32_e32 v18, 16, v14
	v_and_b32_e32 v19, 0xffff0000, v14
	v_mul_f32_e32 v14, 0xbfb8aa3b, v18
	v_exp_f32_e32 v14, v14
	v_mov_b32_e32 v236, v16
	v_mov_b32_e32 v237, v17
	v_lshlrev_b32_e32 v16, 16, v185
	v_and_b32_e32 v17, 0xffff0000, v185
	v_add_f32_e32 v14, 1.0, v14
	v_rcp_f32_e32 v20, v14
	v_mul_f32_e32 v14, 0xbfb8aa3b, v19
	v_exp_f32_e32 v14, v14
	s_nop 0
	v_add_f32_e32 v14, 1.0, v14
	v_rcp_f32_e32 v21, v14
	s_nop 0
	v_pk_mul_f32 v[18:19], v[20:21], v[18:19]
	s_nop 0
	v_pk_mul_f32 v[16:17], v[18:19], v[16:17]
	v_lshlrev_b32_e32 v18, 16, v15
	v_and_b32_e32 v19, 0xffff0000, v15
	v_mul_f32_e32 v15, 0xbfb8aa3b, v18
	v_exp_f32_e32 v15, v15
	v_cvt_pk_bf16_f32 v14, v16, v17
	v_lshlrev_b32_e32 v16, 16, v184
	v_and_b32_e32 v17, 0xffff0000, v184
	v_add_f32_e32 v15, 1.0, v15
	v_rcp_f32_e32 v20, v15
	v_mul_f32_e32 v15, 0xbfb8aa3b, v19
	v_exp_f32_e32 v15, v15
	s_nop 0
	v_add_f32_e32 v15, 1.0, v15
	v_rcp_f32_e32 v21, v15
	s_nop 0
	v_pk_mul_f32 v[18:19], v[20:21], v[18:19]
	s_nop 0
	v_pk_mul_f32 v[16:17], v[18:19], v[16:17]
	s_nop 0
	v_cvt_pk_bf16_f32 v15, v16, v17
	v_lshlrev_b32_e32 v16, 16, v12
	v_and_b32_e32 v17, 0xffff0000, v12
	v_mul_f32_e32 v12, 0xbfb8aa3b, v16
	v_exp_f32_e32 v12, v12
	v_mov_b32_e32 v238, v14
	v_mov_b32_e32 v239, v15
	s_nop 1
	v_permlane32_swap_b32_e32 v236, v238
	v_permlane32_swap_b32_e32 v237, v239
	global_store_dwordx4 v[228:229], v[236:239], off offset:128
	v_lshlrev_b32_e32 v14, 16, v183
	v_and_b32_e32 v15, 0xffff0000, v183
	v_add_f32_e32 v12, 1.0, v12
	v_rcp_f32_e32 v18, v12
	v_mul_f32_e32 v12, 0xbfb8aa3b, v17
	v_exp_f32_e32 v12, v12
	s_nop 0
	v_add_f32_e32 v12, 1.0, v12
	v_rcp_f32_e32 v19, v12
	s_nop 0
	v_pk_mul_f32 v[16:17], v[18:19], v[16:17]
	s_nop 0
	v_pk_mul_f32 v[14:15], v[16:17], v[14:15]
	v_lshlrev_b32_e32 v16, 16, v13
	v_and_b32_e32 v17, 0xffff0000, v13
	v_mul_f32_e32 v13, 0xbfb8aa3b, v16
	v_exp_f32_e32 v13, v13
	v_cvt_pk_bf16_f32 v12, v14, v15
	v_lshlrev_b32_e32 v14, 16, v182
	v_and_b32_e32 v15, 0xffff0000, v182
	v_add_f32_e32 v13, 1.0, v13
	v_rcp_f32_e32 v18, v13
	v_mul_f32_e32 v13, 0xbfb8aa3b, v17
	v_exp_f32_e32 v13, v13
	s_nop 0
	v_add_f32_e32 v13, 1.0, v13
	v_rcp_f32_e32 v19, v13
	s_nop 0
	v_pk_mul_f32 v[16:17], v[18:19], v[16:17]
	s_nop 0
	v_pk_mul_f32 v[14:15], v[16:17], v[14:15]
	s_nop 0
	v_cvt_pk_bf16_f32 v13, v14, v15
	v_lshlrev_b32_e32 v14, 16, v10
	v_and_b32_e32 v15, 0xffff0000, v10
	v_mul_f32_e32 v10, 0xbfb8aa3b, v14
	v_exp_f32_e32 v10, v10
	v_mov_b32_e32 v240, v12
	v_mov_b32_e32 v241, v13
	v_lshlrev_b32_e32 v12, 16, v181
	v_and_b32_e32 v13, 0xffff0000, v181
	v_add_f32_e32 v10, 1.0, v10
	v_rcp_f32_e32 v16, v10
	v_mul_f32_e32 v10, 0xbfb8aa3b, v15
	v_exp_f32_e32 v10, v10
	s_nop 0
	v_add_f32_e32 v10, 1.0, v10
	v_rcp_f32_e32 v17, v10
	s_nop 0
	v_pk_mul_f32 v[14:15], v[16:17], v[14:15]
	s_nop 0
	v_pk_mul_f32 v[12:13], v[14:15], v[12:13]
	v_lshlrev_b32_e32 v14, 16, v11
	v_and_b32_e32 v15, 0xffff0000, v11
	v_mul_f32_e32 v11, 0xbfb8aa3b, v14
	v_exp_f32_e32 v11, v11
	v_cvt_pk_bf16_f32 v10, v12, v13
	v_lshlrev_b32_e32 v12, 16, v180
	v_and_b32_e32 v13, 0xffff0000, v180
	v_add_f32_e32 v11, 1.0, v11
	v_rcp_f32_e32 v16, v11
	v_mul_f32_e32 v11, 0xbfb8aa3b, v15
	v_exp_f32_e32 v11, v11
	s_nop 0
	v_add_f32_e32 v11, 1.0, v11
	v_rcp_f32_e32 v17, v11
	s_nop 0
	v_pk_mul_f32 v[14:15], v[16:17], v[14:15]
	s_nop 0
	v_pk_mul_f32 v[12:13], v[14:15], v[12:13]
	s_nop 0
	v_cvt_pk_bf16_f32 v11, v12, v13
	v_lshlrev_b32_e32 v12, 16, v8
	v_and_b32_e32 v13, 0xffff0000, v8
	v_mul_f32_e32 v8, 0xbfb8aa3b, v12
	v_exp_f32_e32 v8, v8
	v_mov_b32_e32 v242, v10
	v_mov_b32_e32 v243, v11
	s_nop 1
	v_permlane32_swap_b32_e32 v240, v242
	v_permlane32_swap_b32_e32 v241, v243
	global_store_dwordx4 v[228:229], v[240:243], off offset:160
	v_lshlrev_b32_e32 v10, 16, v177
	v_and_b32_e32 v11, 0xffff0000, v177
	v_add_f32_e32 v8, 1.0, v8
	v_rcp_f32_e32 v14, v8
	v_mul_f32_e32 v8, 0xbfb8aa3b, v13
	v_exp_f32_e32 v8, v8
	s_nop 0
	v_add_f32_e32 v8, 1.0, v8
	v_rcp_f32_e32 v15, v8
	s_nop 0
	v_pk_mul_f32 v[12:13], v[14:15], v[12:13]
	s_nop 0
	v_pk_mul_f32 v[10:11], v[12:13], v[10:11]
	v_lshlrev_b32_e32 v12, 16, v9
	v_and_b32_e32 v13, 0xffff0000, v9
	v_mul_f32_e32 v9, 0xbfb8aa3b, v12
	v_exp_f32_e32 v9, v9
	v_cvt_pk_bf16_f32 v8, v10, v11
	v_lshlrev_b32_e32 v10, 16, v176
	v_and_b32_e32 v11, 0xffff0000, v176
	v_add_f32_e32 v9, 1.0, v9
	v_rcp_f32_e32 v14, v9
	v_mul_f32_e32 v9, 0xbfb8aa3b, v13
	v_exp_f32_e32 v9, v9
	s_nop 0
	v_add_f32_e32 v9, 1.0, v9
	v_rcp_f32_e32 v15, v9
	s_nop 0
	v_pk_mul_f32 v[12:13], v[14:15], v[12:13]
	s_nop 0
	v_pk_mul_f32 v[10:11], v[12:13], v[10:11]
	s_nop 0
	v_cvt_pk_bf16_f32 v9, v10, v11
	v_lshlrev_b32_e32 v10, 16, v6
	v_and_b32_e32 v11, 0xffff0000, v6
	v_mul_f32_e32 v6, 0xbfb8aa3b, v10
	v_exp_f32_e32 v6, v6
	v_mov_b32_e32 v244, v8
	v_mov_b32_e32 v245, v9
	v_lshlrev_b32_e32 v8, 16, v175
	v_and_b32_e32 v9, 0xffff0000, v175
	v_add_f32_e32 v6, 1.0, v6
	v_rcp_f32_e32 v12, v6
	v_mul_f32_e32 v6, 0xbfb8aa3b, v11
	v_exp_f32_e32 v6, v6
	s_nop 0
	v_add_f32_e32 v6, 1.0, v6
	v_rcp_f32_e32 v13, v6
	s_nop 0
	v_pk_mul_f32 v[10:11], v[12:13], v[10:11]
	s_nop 0
	v_pk_mul_f32 v[8:9], v[10:11], v[8:9]
	v_lshlrev_b32_e32 v10, 16, v7
	v_and_b32_e32 v11, 0xffff0000, v7
	v_mul_f32_e32 v7, 0xbfb8aa3b, v10
	v_exp_f32_e32 v7, v7
	v_cvt_pk_bf16_f32 v6, v8, v9
	v_lshlrev_b32_e32 v8, 16, v174
	v_and_b32_e32 v9, 0xffff0000, v174
	v_add_f32_e32 v7, 1.0, v7
	v_rcp_f32_e32 v12, v7
	v_mul_f32_e32 v7, 0xbfb8aa3b, v11
	v_exp_f32_e32 v7, v7
	s_nop 0
	v_add_f32_e32 v7, 1.0, v7
	v_rcp_f32_e32 v13, v7
	s_nop 0
	v_pk_mul_f32 v[10:11], v[12:13], v[10:11]
	s_nop 0
	v_pk_mul_f32 v[8:9], v[10:11], v[8:9]
	s_nop 0
	v_cvt_pk_bf16_f32 v7, v8, v9
	v_lshlrev_b32_e32 v8, 16, v4
	v_and_b32_e32 v9, 0xffff0000, v4
	v_mul_f32_e32 v4, 0xbfb8aa3b, v8
	v_exp_f32_e32 v4, v4
	v_mov_b32_e32 v246, v6
	v_mov_b32_e32 v247, v7
	s_nop 1
	v_permlane32_swap_b32_e32 v244, v246
	v_permlane32_swap_b32_e32 v245, v247
	global_store_dwordx4 v[228:229], v[244:247], off offset:192
	v_lshlrev_b32_e32 v6, 16, v173
	v_and_b32_e32 v7, 0xffff0000, v173
	v_add_f32_e32 v4, 1.0, v4
	v_rcp_f32_e32 v10, v4
	v_mul_f32_e32 v4, 0xbfb8aa3b, v9
	v_exp_f32_e32 v4, v4
	s_nop 0
	v_add_f32_e32 v4, 1.0, v4
	v_rcp_f32_e32 v11, v4
	s_nop 0
	v_pk_mul_f32 v[8:9], v[10:11], v[8:9]
	s_nop 0
	v_pk_mul_f32 v[6:7], v[8:9], v[6:7]
	v_lshlrev_b32_e32 v8, 16, v5
	v_and_b32_e32 v9, 0xffff0000, v5
	v_mul_f32_e32 v5, 0xbfb8aa3b, v8
	v_exp_f32_e32 v5, v5
	v_cvt_pk_bf16_f32 v4, v6, v7
	v_lshlrev_b32_e32 v6, 16, v172
	v_and_b32_e32 v7, 0xffff0000, v172
	v_add_f32_e32 v5, 1.0, v5
	v_rcp_f32_e32 v10, v5
	v_mul_f32_e32 v5, 0xbfb8aa3b, v9
	v_exp_f32_e32 v5, v5
	s_nop 0
	v_add_f32_e32 v5, 1.0, v5
	v_rcp_f32_e32 v11, v5
	s_nop 0
	v_pk_mul_f32 v[8:9], v[10:11], v[8:9]
	s_nop 0
	v_pk_mul_f32 v[6:7], v[8:9], v[6:7]
	s_nop 0
	v_cvt_pk_bf16_f32 v5, v6, v7
	v_lshlrev_b32_e32 v6, 16, v0
	v_and_b32_e32 v7, 0xffff0000, v0
	v_mul_f32_e32 v0, 0xbfb8aa3b, v6
	v_exp_f32_e32 v0, v0
	v_mov_b32_e32 v248, v4
	v_mov_b32_e32 v249, v5
	v_lshlrev_b32_e32 v4, 16, v171
	v_and_b32_e32 v5, 0xffff0000, v171
	v_add_f32_e32 v0, 1.0, v0
	v_rcp_f32_e32 v8, v0
	v_mul_f32_e32 v0, 0xbfb8aa3b, v7
	v_exp_f32_e32 v0, v0
	s_nop 0
	v_add_f32_e32 v0, 1.0, v0
	v_rcp_f32_e32 v9, v0
	s_nop 0
	v_pk_mul_f32 v[6:7], v[8:9], v[6:7]
	s_nop 0
	v_pk_mul_f32 v[4:5], v[6:7], v[4:5]
	v_lshlrev_b32_e32 v6, 16, v1
	v_and_b32_e32 v7, 0xffff0000, v1
	v_mul_f32_e32 v1, 0xbfb8aa3b, v6
	v_exp_f32_e32 v1, v1
	v_cvt_pk_bf16_f32 v0, v4, v5
	v_lshlrev_b32_e32 v4, 16, v170
	v_and_b32_e32 v5, 0xffff0000, v170
	v_add_f32_e32 v1, 1.0, v1
	v_rcp_f32_e32 v8, v1
	v_mul_f32_e32 v1, 0xbfb8aa3b, v7
	v_exp_f32_e32 v1, v1
	s_nop 0
	v_add_f32_e32 v1, 1.0, v1
	v_rcp_f32_e32 v9, v1
	s_nop 0
	v_pk_mul_f32 v[6:7], v[8:9], v[6:7]
	s_nop 0
	v_pk_mul_f32 v[4:5], v[6:7], v[4:5]
	s_nop 0
	v_cvt_pk_bf16_f32 v1, v4, v5
	v_mov_b32_e32 v250, v0
	v_mov_b32_e32 v251, v1
	s_nop 1
	v_permlane32_swap_b32_e32 v248, v250
	v_permlane32_swap_b32_e32 v249, v251
	global_store_dwordx4 v[228:229], v[248:251], off offset:224
